# S5 unit set-up: cache-warming touch of the group's B and C constant rows ahead of the compiler's serialized load pairs
# baseline (speedup 1.0000x reference)
; __device__ __forceinline__ void s5_phase(LAS unsigned char* lds, const bf16_t* USSM, const float* S5A, const float* S5B, const float* c_re, const float* c_im, const float* dskip,
;                                          bf16_t* YSSM, int tid, int lane, int wave) {
;     ...
;     for (int bg = blockIdx.x; bg < 256; bg += gridDim.x) {
;         const int b = bg >> 6, g = bg & 63;
;         __syncthreads();
;         const float are = S5A[(g * 64 + lane) * 2], aim = S5A[(g * 64 + lane) * 2 + 1];
;         bf16x8 bfr[8], cfr[4];
; #pragma unroll
;         for (int nt = 0; nt < 8; ++nt) { const int pp = nt * 16 + r16, p = pp & 63, im = pp >> 6; bfr[nt] = q4 < 2 ? pack_bf8(S5B + (size_t)(g * 64 + p) * 32 + im * 16 + q4 * 8, 1.f) : zf; }
; #pragma unroll
;         for (int ks = 0; ks < 4; ++ks) { const int pp = ks * 32 + q4 * 8, p = pp & 63, im = pp >> 6; cfr[ks] = pack_bf8((im ? c_im : c_re) + (size_t)(g * 16 + r16) * 64 + p, im ? -1.f : 1.f); }
.LBB0_568:
	s_and_b32 s6, s43, 63
	s_lshl_b32 s12, s6, 6
	v_lshlrev_b32_e32 v226, 4, v106
	v_add_u32_e32 v227, 0x1000, v226
	s_lshl_b32 s14, s6, 13
	s_add_u32 s14, s62, s14
	s_addc_u32 s15, s63, 0
	global_load_dwordx4 v[222:225], v226, s[14:15] offset:0
	global_load_dwordx4 v[222:225], v226, s[14:15] offset:1024
	global_load_dwordx4 v[222:225], v226, s[14:15] offset:2048
	global_load_dwordx4 v[222:225], v226, s[14:15] offset:3072
	global_load_dwordx4 v[222:225], v227, s[14:15] offset:0
	global_load_dwordx4 v[222:225], v227, s[14:15] offset:1024
	global_load_dwordx4 v[222:225], v227, s[14:15] offset:2048
	global_load_dwordx4 v[222:225], v227, s[14:15] offset:3072
	v_lshl_or_b32 v228, s6, 12, v117
	v_mov_b32_e32 v229, 0
	v_lshl_add_u64 v[230:231], v[88:89], 0, v[228:229]
	global_load_dwordx4 v[222:225], v[230:231], off
	global_load_dwordx4 v[222:225], v[230:231], off offset:128
	v_lshl_add_u64 v[230:231], v[90:91], 0, v[228:229]
	global_load_dwordx4 v[222:225], v[230:231], off
	global_load_dwordx4 v[222:225], v[230:231], off offset:128
	v_or_b32_e32 v13, s12, v106
	v_lshlrev_b32_e32 v0, 3, v13
	s_barrier
	global_load_dwordx2 v[94:95], v0, s[94:95]
	v_or_b32_e32 v0, s12, v81
	v_lshlrev_b32_e32 v82, 7, v0
	v_mov_b32_e32 v0, 0
	v_mov_b32_e32 v1, 0
	v_mov_b32_e32 v2, 0
	v_mov_b32_e32 v3, 0
	s_and_saveexec_b64 s[14:15], s[0:1]
	s_cbranch_execz .LBB0_570
	v_lshl_add_u64 v[4:5], v[86:87], 0, v[82:83]
	global_load_dwordx4 v[0:3], v[4:5], off
	s_nop 0
	global_load_dwordx4 v[4:7], v[4:5], off offset:16
	s_waitcnt vmcnt(1)
	v_cvt_pk_bf16_f32 v0, v0, v1
	v_cvt_pk_bf16_f32 v1, v2, v3
	s_waitcnt vmcnt(0)
	v_cvt_pk_bf16_f32 v2, v4, v5
	v_cvt_pk_bf16_f32 v3, v6, v7
